# v083: v081 + nt hint on the A-operand (gathered cache rows) LDS-DMA loads of the three k_inv filler instances
# baseline (speedup 1.0000x reference)
.LBB0_644:
	v_readlane_b32 s0, v253, 26
	v_readlane_b32 s1, v253, 27
	s_and_b64 s[0:1], s[0:1], s[6:7]
	s_andn2_b64 vcc, exec, s[0:1]
	s_cbranch_vccnz .LBB0_674
	v_mov_b32_e32 v1, v0
	s_movk_i32 s0, 0x120
	s_waitcnt lgkmcnt(0)
	v_bfe_i32 v5, v1, 27, 1
	v_lshlrev_b32_e32 v3, 4, v1
	v_lshrrev_b32_e32 v5, 22, v5
	v_add_u32_e32 v5, v3, v5
	v_and_b32_e32 v5, 0xfffffc00, v5
	v_ashrrev_i32_e32 v4, 31, v1
	v_sub_u32_e32 v5, v3, v5
	v_lshrrev_b32_e32 v4, 26, v4
	v_lshrrev_b32_e32 v6, 4, v5
	v_add_u32_e32 v4, v1, v4
	v_bitop3_b32 v6, v6, v5, 32 bitop3:0x6c
	v_ashrrev_i32_e32 v5, 31, v5
	v_ashrrev_i32_e32 v4, 6, v4
	v_lshrrev_b32_e32 v5, 26, v5
	v_lshlrev_b32_e32 v7, 3, v4
	v_add_u32_e32 v5, v6, v5
	v_and_b32_e32 v7, -16, v7
	v_ashrrev_i32_e32 v5, 6, v5
	v_add_u32_e32 v7, v5, v7
	v_mul_i32_i24_e32 v5, 64, v5
	v_lshlrev_b32_e32 v4, 5, v4
	v_sub_u32_e32 v5, v6, v5
	v_and_b32_e32 v4, 32, v4
	v_ashrrev_i16_sdwa v5, v235, sext(v5) dst_sel:DWORD dst_unused:UNUSED_PAD src0_sel:DWORD src1_sel:BYTE_0
	v_add_u32_sdwa v4, v4, sext(v5) dst_sel:DWORD dst_unused:UNUSED_PAD src0_sel:DWORD src1_sel:WORD_0
	v_mul_lo_u32 v5, v7, s0
	v_add_lshl_u32 v132, v4, v5, 1
	v_lshlrev_b32_e32 v5, 9, v7
	v_add_u32_e32 v3, 0x2000, v3
	v_lshl_add_u32 v134, v4, 1, v5
	v_ashrrev_i32_e32 v4, 31, v3
	v_lshrrev_b32_e32 v4, 22, v4
	v_add_u32_e32 v4, v3, v4
	v_ashrrev_i32_e32 v4, 10, v4
	v_mul_i32_i24_e32 v5, 0x400, v4
	v_sub_u32_e32 v3, v3, v5
	v_lshrrev_b32_e32 v5, 4, v3
	v_bitop3_b32 v3, v5, v3, 32 bitop3:0x6c
	v_ashrrev_i32_e32 v6, 31, v3
	v_lshrrev_b32_e32 v6, 26, v6
	s_add_u32 s46, s22, 0x1d123c00
	v_add_u32_e32 v6, v3, v6
	s_addc_u32 s47, s23, 0
	v_lshlrev_b32_e32 v5, 3, v4
	v_ashrrev_i32_e32 v7, 6, v6
	v_and_b32_e32 v6, 0xc0, v6
	s_add_u32 s48, s22, 0x561dc00
	v_readfirstlane_b32 s50, v1
	v_and_b32_e32 v5, -16, v5
	v_lshlrev_b32_e32 v4, 5, v4
	v_sub_u32_e32 v3, v3, v6
	s_addc_u32 s49, s23, 0
	v_add_u32_e32 v5, v7, v5
	v_and_b32_e32 v4, 32, v4
	v_ashrrev_i16_sdwa v3, v235, sext(v3) dst_sel:DWORD dst_unused:UNUSED_PAD src0_sel:DWORD src1_sel:BYTE_0
	s_ashr_i32 s9, s50, 6
	s_ashr_i32 s8, s50, 8
	v_add_u32_sdwa v3, v4, sext(v3) dst_sel:DWORD dst_unused:UNUSED_PAD src0_sel:DWORD src1_sel:WORD_0
	v_mul_lo_u32 v4, v5, s0
	s_lshl_b32 s51, s9, 10
	v_readlane_b32 s0, v254, 43
	v_readlane_b32 s1, v254, 44
	s_add_u32 s0, s48, s0
	s_addc_u32 s1, s49, s1
	s_add_i32 s52, s51, 0
	v_add_lshl_u32 v136, v3, v4, 1
	v_lshlrev_b32_e32 v4, 9, v5
	s_mov_b64 s[14:15], s[0:1]
	s_add_i32 m0, s52, 0x10000
	v_lshl_add_u32 v138, v3, 1, v4
	s_nop 0
	global_load_lds_dwordx4 v134, s[14:15]
	s_add_i32 m0, s52, 0x12000
	s_nop 0
	global_load_lds_dwordx4 v138, s[14:15]
	v_readlane_b32 s15, v254, 40
	s_mul_i32 s14, s15, 0x24000
	s_add_u32 s14, s46, s14
	s_mul_hi_i32 s15, s15, 0x24000
	s_addc_u32 s15, s47, s15
	s_mov_b64 s[16:17], s[14:15]
	s_mov_b32 m0, s52
	s_add_i32 s53, s52, 0x2000
	s_nop 0
	global_load_lds_dwordx4 v132, s[16:17] nt
	s_mov_b32 m0, s53
	s_nop 0
	global_load_lds_dwordx4 v136, s[16:17] nt
	s_add_u32 s16, s0, 0x10000
	s_addc_u32 s17, s1, 0
	s_add_i32 m0, s52, 0x14000
	s_nop 0
	global_load_lds_dwordx4 v134, s[16:17]
	s_add_i32 m0, s52, 0x16000
	s_nop 0
	global_load_lds_dwordx4 v138, s[16:17]
	s_add_u32 s16, s14, 0x12000
	s_addc_u32 s17, s15, 0
	s_add_i32 s55, s52, 0x4000
	s_mov_b32 m0, s55
	s_add_i32 s56, s52, 0x6000
	s_cmp_lg_u32 s8, 1
	global_load_lds_dwordx4 v132, s[16:17] nt
	s_mov_b32 m0, s56
	s_nop 0
	global_load_lds_dwordx4 v136, s[16:17] nt
	s_cbranch_scc1 .LBB0_647
	s_barrier

.LBB0_654:
	s_add_u32 s36, s14, s26
	s_addc_u32 s37, s15, s27
	s_add_u32 s38, s36, 0x100
	s_addc_u32 s39, s37, 0
	s_and_b64 s[30:31], s[28:29], exec
	s_cselect_b32 s41, s19, s39
	s_cselect_b32 s40, s18, s38
	s_add_u32 s26, s0, s26
	s_addc_u32 s27, s1, s27
	s_add_u32 s30, s26, 0x100
	s_addc_u32 s31, s27, 0
	s_add_u32 s26, s40, 0x80
	s_addc_u32 s27, s41, 0
	s_add_i32 s81, 0, 0x10000
	s_and_b64 s[28:29], s[28:29], exec
	s_cselect_b32 s43, s17, s31
	s_cselect_b32 s42, s23, s30
	s_add_u32 s44, s36, 0x12080
	s_addc_u32 s45, s37, 0
	s_add_i32 s86, s81, s51
	s_add_i32 m0, s52, 0xc000
	s_add_i32 s87, s52, 0xe000
	s_add_i32 s85, 0, 0x14000
	s_add_i32 s84, s86, 0x2000
	s_add_u32 s38, s42, 0x10000
	s_addc_u32 s39, s43, 0
	s_add_i32 s82, s85, s51
	s_add_i32 s80, s82, 0x2000
	s_add_i32 s79, 0, 0x18000
	v_add_u32_e32 v152, s81, v1
	s_add_u32 s36, s40, 0x12000
	ds_read_b128 v[140:143], v152
	ds_read_b128 v[144:147], v152 offset:1024
	ds_read_b128 v[148:151], v152 offset:2048
	ds_read_b128 v[152:155], v152 offset:3072
	s_addc_u32 s37, s41, 0
	s_add_i32 s75, 0, 0x1c000
	s_add_u32 s30, s42, 0x80
	s_addc_u32 s31, s43, 0
	s_add_i32 s78, s79, s51
	s_add_i32 s74, s78, 0x2000
	s_add_u32 s28, s42, 0x10080
	s_addc_u32 s29, s43, 0
	s_add_i32 s83, s75, s51
	s_add_i32 s81, s83, 0x2000
	ds_read_b128 v[156:159], v3
	ds_read_b128 v[160:163], v3 offset:1024
	ds_read_b128 v[164:167], v3 offset:2048
	ds_read_b128 v[168:171], v3 offset:3072
	ds_read_b128 v[172:175], v3 offset:4096
	ds_read_b128 v[176:179], v3 offset:5120
	ds_read_b128 v[180:183], v3 offset:6144
	ds_read_b128 v[184:187], v3 offset:7168
	s_nop 0
	global_load_lds_dwordx4 v132, s[44:45] nt
	s_mov_b32 m0, s87
	s_nop 0
	global_load_lds_dwordx4 v136, s[44:45] nt
	s_waitcnt lgkmcnt(8)
	s_barrier
	s_waitcnt lgkmcnt(0)
	s_setprio 1
	s_waitcnt lgkmcnt(0)
	v_mfma_f32_16x16x32_bf16 v[128:131], v[140:143], v[156:159], v[128:131]
	v_mfma_f32_16x16x32_bf16 v[124:127], v[148:151], v[156:159], v[124:127]
	v_mfma_f32_16x16x32_bf16 v[112:115], v[140:143], v[164:167], v[112:115]
	v_mfma_f32_16x16x32_bf16 v[108:111], v[148:151], v[164:167], v[108:111]
	v_mfma_f32_16x16x32_bf16 v[96:99], v[140:143], v[172:175], v[96:99]
	v_mfma_f32_16x16x32_bf16 v[92:95], v[148:151], v[172:175], v[92:95]
	v_mfma_f32_16x16x32_bf16 v[80:83], v[140:143], v[180:183], v[80:83]
	v_mfma_f32_16x16x32_bf16 v[76:79], v[148:151], v[180:183], v[76:79]
	v_mfma_f32_16x16x32_bf16 v[128:131], v[144:147], v[160:163], v[128:131]
	v_mfma_f32_16x16x32_bf16 v[124:127], v[152:155], v[160:163], v[124:127]
	v_mfma_f32_16x16x32_bf16 v[112:115], v[144:147], v[168:171], v[112:115]
	v_mfma_f32_16x16x32_bf16 v[108:111], v[152:155], v[168:171], v[108:111]
	v_mfma_f32_16x16x32_bf16 v[96:99], v[144:147], v[176:179], v[96:99]
	v_mfma_f32_16x16x32_bf16 v[92:95], v[152:155], v[176:179], v[92:95]
	v_mfma_f32_16x16x32_bf16 v[80:83], v[144:147], v[184:187], v[80:83]
	v_mfma_f32_16x16x32_bf16 v[76:79], v[152:155], v[184:187], v[76:79]
	s_setprio 0
	s_barrier
	v_add_u32_e32 v214, s85, v1
	s_mov_b32 m0, s86
	ds_read_b128 v[188:191], v214
	ds_read_b128 v[192:195], v214 offset:1024
	ds_read_b128 v[210:213], v214 offset:2048
	ds_read_b128 v[214:217], v214 offset:3072
	s_nop 0
	global_load_lds_dwordx4 v134, s[42:43]
	s_mov_b32 m0, s84
	s_nop 0
	global_load_lds_dwordx4 v138, s[42:43]
	s_barrier
	s_waitcnt lgkmcnt(0)
	s_setprio 1
	s_waitcnt lgkmcnt(0)
	v_mfma_f32_16x16x32_bf16 v[120:123], v[188:191], v[156:159], v[120:123]
	v_mfma_f32_16x16x32_bf16 v[116:119], v[210:213], v[156:159], v[116:119]
	v_mfma_f32_16x16x32_bf16 v[104:107], v[188:191], v[164:167], v[104:107]
	v_mfma_f32_16x16x32_bf16 v[100:103], v[210:213], v[164:167], v[100:103]
	v_mfma_f32_16x16x32_bf16 v[88:91], v[188:191], v[172:175], v[88:91]
	v_mfma_f32_16x16x32_bf16 v[84:87], v[210:213], v[172:175], v[84:87]
	v_mfma_f32_16x16x32_bf16 v[72:75], v[188:191], v[180:183], v[72:75]
	v_mfma_f32_16x16x32_bf16 v[68:71], v[210:213], v[180:183], v[68:71]
	v_mfma_f32_16x16x32_bf16 v[120:123], v[192:195], v[160:163], v[120:123]
	v_mfma_f32_16x16x32_bf16 v[116:119], v[214:217], v[160:163], v[116:119]
	v_mfma_f32_16x16x32_bf16 v[104:107], v[192:195], v[168:171], v[104:107]
	v_mfma_f32_16x16x32_bf16 v[100:103], v[214:217], v[168:171], v[100:103]
	v_mfma_f32_16x16x32_bf16 v[88:91], v[192:195], v[176:179], v[88:91]
	v_mfma_f32_16x16x32_bf16 v[84:87], v[214:217], v[176:179], v[84:87]
	v_mfma_f32_16x16x32_bf16 v[72:75], v[192:195], v[184:187], v[72:75]
	v_mfma_f32_16x16x32_bf16 v[68:71], v[214:217], v[184:187], v[68:71]
	s_setprio 0
	s_mov_b32 m0, s52
	s_barrier
	ds_read_b128 v[156:159], v3 offset:16384
	ds_read_b128 v[160:163], v3 offset:17408
	ds_read_b128 v[164:167], v3 offset:18432
	ds_read_b128 v[168:171], v3 offset:19456
	ds_read_b128 v[172:175], v3 offset:20480
	ds_read_b128 v[176:179], v3 offset:21504
	ds_read_b128 v[180:183], v3 offset:22528
	ds_read_b128 v[184:187], v3 offset:23552
	s_nop 0
	global_load_lds_dwordx4 v132, s[40:41] nt
	s_mov_b32 m0, s53
	s_nop 0
	global_load_lds_dwordx4 v136, s[40:41] nt
	s_barrier
	s_waitcnt lgkmcnt(0)
	s_setprio 1
	s_waitcnt lgkmcnt(0)
	v_mfma_f32_16x16x32_bf16 v[64:67], v[140:143], v[156:159], v[64:67]
	v_mfma_f32_16x16x32_bf16 v[60:63], v[148:151], v[156:159], v[60:63]
	v_mfma_f32_16x16x32_bf16 v[48:51], v[140:143], v[164:167], v[48:51]
	v_mfma_f32_16x16x32_bf16 v[44:47], v[148:151], v[164:167], v[44:47]
	v_mfma_f32_16x16x32_bf16 v[32:35], v[140:143], v[172:175], v[32:35]
	v_mfma_f32_16x16x32_bf16 v[28:31], v[148:151], v[172:175], v[28:31]
	v_mfma_f32_16x16x32_bf16 v[16:19], v[140:143], v[180:183], v[16:19]
	v_mfma_f32_16x16x32_bf16 v[12:15], v[148:151], v[180:183], v[12:15]
	v_mfma_f32_16x16x32_bf16 v[64:67], v[144:147], v[160:163], v[64:67]
	v_mfma_f32_16x16x32_bf16 v[60:63], v[152:155], v[160:163], v[60:63]
	v_mfma_f32_16x16x32_bf16 v[48:51], v[144:147], v[168:171], v[48:51]
	v_mfma_f32_16x16x32_bf16 v[44:47], v[152:155], v[168:171], v[44:47]
	v_mfma_f32_16x16x32_bf16 v[32:35], v[144:147], v[176:179], v[32:35]
	v_mfma_f32_16x16x32_bf16 v[28:31], v[152:155], v[176:179], v[28:31]
	v_mfma_f32_16x16x32_bf16 v[16:19], v[144:147], v[184:187], v[16:19]
	v_mfma_f32_16x16x32_bf16 v[12:15], v[152:155], v[184:187], v[12:15]
	s_setprio 0
	s_barrier
	s_mov_b32 m0, s82
	s_nop 0
	global_load_lds_dwordx4 v134, s[38:39]
	s_mov_b32 m0, s80
	s_nop 0
	global_load_lds_dwordx4 v138, s[38:39]
	s_waitcnt vmcnt(6)
	s_barrier
	s_setprio 1
	v_mfma_f32_16x16x32_bf16 v[56:59], v[188:191], v[156:159], v[56:59]
	v_mfma_f32_16x16x32_bf16 v[52:55], v[210:213], v[156:159], v[52:55]
	v_mfma_f32_16x16x32_bf16 v[40:43], v[188:191], v[164:167], v[40:43]
	v_mfma_f32_16x16x32_bf16 v[36:39], v[210:213], v[164:167], v[36:39]
	v_mfma_f32_16x16x32_bf16 v[24:27], v[188:191], v[172:175], v[24:27]
	v_mfma_f32_16x16x32_bf16 v[20:23], v[210:213], v[172:175], v[20:23]
	v_mfma_f32_16x16x32_bf16 v[8:11], v[188:191], v[180:183], v[8:11]
	v_mfma_f32_16x16x32_bf16 v[4:7], v[210:213], v[180:183], v[4:7]
	v_mfma_f32_16x16x32_bf16 v[56:59], v[192:195], v[160:163], v[56:59]
	v_mfma_f32_16x16x32_bf16 v[52:55], v[214:217], v[160:163], v[52:55]
	v_mfma_f32_16x16x32_bf16 v[40:43], v[192:195], v[168:171], v[40:43]
	v_mfma_f32_16x16x32_bf16 v[36:39], v[214:217], v[168:171], v[36:39]
	v_mfma_f32_16x16x32_bf16 v[24:27], v[192:195], v[176:179], v[24:27]
	v_mfma_f32_16x16x32_bf16 v[20:23], v[214:217], v[176:179], v[20:23]
	v_mfma_f32_16x16x32_bf16 v[8:11], v[192:195], v[184:187], v[8:11]
	v_mfma_f32_16x16x32_bf16 v[4:7], v[214:217], v[184:187], v[4:7]
	s_setprio 0
	v_add_u32_e32 v152, s79, v1
	s_barrier
	ds_read_b128 v[140:143], v152
	ds_read_b128 v[144:147], v152 offset:1024
	ds_read_b128 v[148:151], v152 offset:2048
	ds_read_b128 v[152:155], v152 offset:3072
	s_mov_b32 m0, s55
	ds_read_b128 v[156:159], v3 offset:32768
	ds_read_b128 v[160:163], v3 offset:33792
	ds_read_b128 v[164:167], v3 offset:34816
	ds_read_b128 v[168:171], v3 offset:35840
	ds_read_b128 v[172:175], v3 offset:36864
	ds_read_b128 v[176:179], v3 offset:37888
	ds_read_b128 v[180:183], v3 offset:38912
	ds_read_b128 v[184:187], v3 offset:39936
	s_nop 0
	global_load_lds_dwordx4 v132, s[36:37] nt
	s_mov_b32 m0, s56
	s_nop 0
	global_load_lds_dwordx4 v136, s[36:37] nt
	s_waitcnt lgkmcnt(8)
	s_barrier
	s_waitcnt lgkmcnt(0)
	s_setprio 1
	s_waitcnt lgkmcnt(0)
	v_mfma_f32_16x16x32_bf16 v[128:131], v[140:143], v[156:159], v[128:131]
	v_mfma_f32_16x16x32_bf16 v[124:127], v[148:151], v[156:159], v[124:127]
	v_mfma_f32_16x16x32_bf16 v[112:115], v[140:143], v[164:167], v[112:115]
	v_mfma_f32_16x16x32_bf16 v[108:111], v[148:151], v[164:167], v[108:111]
	v_mfma_f32_16x16x32_bf16 v[96:99], v[140:143], v[172:175], v[96:99]
	v_mfma_f32_16x16x32_bf16 v[92:95], v[148:151], v[172:175], v[92:95]
	v_mfma_f32_16x16x32_bf16 v[80:83], v[140:143], v[180:183], v[80:83]
	v_mfma_f32_16x16x32_bf16 v[76:79], v[148:151], v[180:183], v[76:79]
	v_mfma_f32_16x16x32_bf16 v[128:131], v[144:147], v[160:163], v[128:131]
	v_mfma_f32_16x16x32_bf16 v[124:127], v[152:155], v[160:163], v[124:127]
	v_mfma_f32_16x16x32_bf16 v[112:115], v[144:147], v[168:171], v[112:115]
	v_mfma_f32_16x16x32_bf16 v[108:111], v[152:155], v[168:171], v[108:111]
	v_mfma_f32_16x16x32_bf16 v[96:99], v[144:147], v[176:179], v[96:99]
	v_mfma_f32_16x16x32_bf16 v[92:95], v[152:155], v[176:179], v[92:95]
	v_mfma_f32_16x16x32_bf16 v[80:83], v[144:147], v[184:187], v[80:83]
	v_mfma_f32_16x16x32_bf16 v[76:79], v[152:155], v[184:187], v[76:79]
	s_setprio 0
	s_barrier
	v_add_u32_e32 v214, s75, v1
	s_mov_b32 m0, s78
	ds_read_b128 v[188:191], v214
	ds_read_b128 v[192:195], v214 offset:1024
	ds_read_b128 v[210:213], v214 offset:2048
	ds_read_b128 v[214:217], v214 offset:3072
	s_nop 0
	global_load_lds_dwordx4 v134, s[30:31]
	s_mov_b32 m0, s74
	s_nop 0
	global_load_lds_dwordx4 v138, s[30:31]
	s_barrier
	s_waitcnt lgkmcnt(0)
	s_setprio 1
	s_waitcnt lgkmcnt(0)
	v_mfma_f32_16x16x32_bf16 v[120:123], v[188:191], v[156:159], v[120:123]
	v_mfma_f32_16x16x32_bf16 v[116:119], v[210:213], v[156:159], v[116:119]
	v_mfma_f32_16x16x32_bf16 v[104:107], v[188:191], v[164:167], v[104:107]
	v_mfma_f32_16x16x32_bf16 v[100:103], v[210:213], v[164:167], v[100:103]
	v_mfma_f32_16x16x32_bf16 v[88:91], v[188:191], v[172:175], v[88:91]
	v_mfma_f32_16x16x32_bf16 v[84:87], v[210:213], v[172:175], v[84:87]
	v_mfma_f32_16x16x32_bf16 v[72:75], v[188:191], v[180:183], v[72:75]
	v_mfma_f32_16x16x32_bf16 v[68:71], v[210:213], v[180:183], v[68:71]
	v_mfma_f32_16x16x32_bf16 v[120:123], v[192:195], v[160:163], v[120:123]
	v_mfma_f32_16x16x32_bf16 v[116:119], v[214:217], v[160:163], v[116:119]
	v_mfma_f32_16x16x32_bf16 v[104:107], v[192:195], v[168:171], v[104:107]
	v_mfma_f32_16x16x32_bf16 v[100:103], v[214:217], v[168:171], v[100:103]
	v_mfma_f32_16x16x32_bf16 v[88:91], v[192:195], v[176:179], v[88:91]
	v_mfma_f32_16x16x32_bf16 v[84:87], v[214:217], v[176:179], v[84:87]
	v_mfma_f32_16x16x32_bf16 v[72:75], v[192:195], v[184:187], v[72:75]
	v_mfma_f32_16x16x32_bf16 v[68:71], v[214:217], v[184:187], v[68:71]
	s_setprio 0
	s_mov_b32 m0, s65
	s_barrier
	ds_read_b128 v[156:159], v3 offset:49152
	ds_read_b128 v[160:163], v3 offset:50176
	ds_read_b128 v[164:167], v3 offset:51200
	ds_read_b128 v[168:171], v3 offset:52224
	ds_read_b128 v[172:175], v3 offset:53248
	ds_read_b128 v[176:179], v3 offset:54272
	ds_read_b128 v[180:183], v3 offset:55296
	ds_read_b128 v[184:187], v3 offset:56320
	s_nop 0
	global_load_lds_dwordx4 v132, s[26:27] nt
	s_mov_b32 m0, s67
	s_nop 0
	global_load_lds_dwordx4 v136, s[26:27] nt
	s_barrier
	s_waitcnt lgkmcnt(0)
	s_setprio 1
	s_waitcnt lgkmcnt(0)
	v_mfma_f32_16x16x32_bf16 v[64:67], v[140:143], v[156:159], v[64:67]
	v_mfma_f32_16x16x32_bf16 v[60:63], v[148:151], v[156:159], v[60:63]
	v_mfma_f32_16x16x32_bf16 v[48:51], v[140:143], v[164:167], v[48:51]
	v_mfma_f32_16x16x32_bf16 v[44:47], v[148:151], v[164:167], v[44:47]
	v_mfma_f32_16x16x32_bf16 v[32:35], v[140:143], v[172:175], v[32:35]
	v_mfma_f32_16x16x32_bf16 v[28:31], v[148:151], v[172:175], v[28:31]
	v_mfma_f32_16x16x32_bf16 v[16:19], v[140:143], v[180:183], v[16:19]
	v_mfma_f32_16x16x32_bf16 v[12:15], v[148:151], v[180:183], v[12:15]
	v_mfma_f32_16x16x32_bf16 v[64:67], v[144:147], v[160:163], v[64:67]
	v_mfma_f32_16x16x32_bf16 v[60:63], v[152:155], v[160:163], v[60:63]
	v_mfma_f32_16x16x32_bf16 v[48:51], v[144:147], v[168:171], v[48:51]
	v_mfma_f32_16x16x32_bf16 v[44:47], v[152:155], v[168:171], v[44:47]
	v_mfma_f32_16x16x32_bf16 v[32:35], v[144:147], v[176:179], v[32:35]
	v_mfma_f32_16x16x32_bf16 v[28:31], v[152:155], v[176:179], v[28:31]
	v_mfma_f32_16x16x32_bf16 v[16:19], v[144:147], v[184:187], v[16:19]
	v_mfma_f32_16x16x32_bf16 v[12:15], v[152:155], v[184:187], v[12:15]
	s_setprio 0
	s_barrier
	s_mov_b32 m0, s83
	s_nop 0
	global_load_lds_dwordx4 v134, s[28:29]
	s_mov_b32 m0, s81
	s_nop 0
	global_load_lds_dwordx4 v138, s[28:29]
	s_waitcnt vmcnt(6)
	s_barrier
	s_setprio 1
	v_mfma_f32_16x16x32_bf16 v[56:59], v[188:191], v[156:159], v[56:59]
	v_mfma_f32_16x16x32_bf16 v[52:55], v[210:213], v[156:159], v[52:55]
	v_mfma_f32_16x16x32_bf16 v[40:43], v[188:191], v[164:167], v[40:43]
	v_mfma_f32_16x16x32_bf16 v[36:39], v[210:213], v[164:167], v[36:39]
	v_mfma_f32_16x16x32_bf16 v[24:27], v[188:191], v[172:175], v[24:27]
	v_mfma_f32_16x16x32_bf16 v[20:23], v[210:213], v[172:175], v[20:23]
	v_mfma_f32_16x16x32_bf16 v[8:11], v[188:191], v[180:183], v[8:11]
	v_mfma_f32_16x16x32_bf16 v[4:7], v[210:213], v[180:183], v[4:7]
	v_mfma_f32_16x16x32_bf16 v[56:59], v[192:195], v[160:163], v[56:59]
	v_mfma_f32_16x16x32_bf16 v[52:55], v[214:217], v[160:163], v[52:55]
	v_mfma_f32_16x16x32_bf16 v[40:43], v[192:195], v[168:171], v[40:43]
	v_mfma_f32_16x16x32_bf16 v[36:39], v[214:217], v[168:171], v[36:39]
	v_mfma_f32_16x16x32_bf16 v[24:27], v[192:195], v[176:179], v[24:27]
	v_mfma_f32_16x16x32_bf16 v[20:23], v[214:217], v[176:179], v[20:23]
	v_mfma_f32_16x16x32_bf16 v[8:11], v[192:195], v[184:187], v[8:11]
	v_mfma_f32_16x16x32_bf16 v[4:7], v[214:217], v[184:187], v[4:7]
	s_setprio 0
	s_andn2_b64 vcc, exec, s[24:25]
	s_mov_b64 s[28:29], -1
	s_mov_b64 s[24:25], 0
	s_mov_b64 s[26:27], 0x100
	s_barrier
	s_cbranch_vccz .LBB0_654
	v_mov_b32_e32 v141, v0
	s_ashr_i32 s23, s22, 31
	v_readfirstlane_b32 s0, v141
	s_bfe_u32 s17, s0, 0x20006
	s_ashr_i32 s0, s0, 2
	s_andn2_b32 s0, s0, 63
	s_ashr_i32 s1, s0, 31
	s_lshl_b64 s[14:15], s[22:23], 10
	s_add_u32 s24, s57, s14
	s_addc_u32 s25, s62, s15
	s_lshl_b64 s[14:15], s[0:1], 2
	v_and_b32_e32 v142, 15, v141
	s_add_u32 s24, s24, s14
	s_addc_u32 s25, s25, s15
	v_lshlrev_b32_e32 v140, 2, v142
	s_min_u32 s100, s72, 0x7ff
	s_lshl_b32 s100, s100, 10
	v_and_b32_e32 v210, 7, v0
	v_lshlrev_b32_e32 v210, 7, v210
	v_add_u32_e32 v210, s100, v210
	s_mov_b32 s100, s57
	s_mov_b32 s101, s62
	global_load_dword v211, v210, s[100:101]
	global_load_dword v150, v140, s[24:25] offset:64
	global_load_dword v149, v140, s[24:25] offset:128
	global_load_dword v148, v140, s[24:25] offset:192
	global_load_dword v147, v140, s[24:25] offset:512
	global_load_dword v146, v140, s[24:25] offset:576
	global_load_dword v145, v140, s[24:25] offset:640
	global_load_dword v144, v140, s[24:25] offset:704
	v_mul_f32_e32 v129, v129, v129
	v_mul_f32_e32 v125, v125, v125
	v_mul_f32_e32 v121, v121, v121
	v_mul_f32_e32 v117, v117, v117
	v_fmac_f32_e32 v129, v128, v128
	v_mul_f32_e32 v128, v131, v131
	v_fmac_f32_e32 v125, v124, v124
	v_mul_f32_e32 v124, v127, v127
	v_fmac_f32_e32 v121, v120, v120
	v_mul_f32_e32 v120, v123, v123
	v_fmac_f32_e32 v117, v116, v116
	v_mul_f32_e32 v116, v119, v119
	v_fmac_f32_e32 v128, v130, v130
	v_fmac_f32_e32 v124, v126, v126
	v_fmac_f32_e32 v120, v122, v122
	v_fmac_f32_e32 v116, v118, v118
	v_add_f32_e32 v128, v129, v128
	v_add_f32_e32 v124, v125, v124
	v_add_f32_e32 v120, v121, v120
	v_add_f32_e32 v116, v117, v116
	v_add_f32_e32 v124, v128, v124
	v_add_f32_e32 v116, v120, v116
	v_add_f32_e32 v117, v124, v116
	v_mov_b32_e32 v118, v117
	s_nop 1
	v_permlane16_swap_b32 v118, v117
	v_and_b32_e32 v152, 64, v236
	v_xor_b32_e32 v151, 32, v236
	v_add_u32_e32 v152, 64, v152
	v_cmp_lt_i32_e32 vcc, v151, v152
	s_lshl_b32 s14, s73, 2
	s_or_b32 s26, s17, s14
	v_cndmask_b32_e32 v116, v236, v151, vcc
	s_lshl_b64 s[14:15], s[22:23], 8
	v_lshlrev_b32_e32 v116, 2, v116
	s_waitcnt lgkmcnt(0)
	v_add_f32_e32 v117, v117, v118
	s_add_u32 s0, s14, s0
	v_mov_b32_e32 v118, v117
	s_nop 1
	v_permlane32_swap_b32 v118, v117
	s_addc_u32 s1, s15, s1
	s_ashr_i32 s27, s26, 31
	v_or_b32_e32 v143, s0, v142
	v_mov_b32_e32 v142, s1
	s_lshl_b64 s[0:1], s[26:27], 2
	v_and_b32_e32 v119, 48, v141
	s_add_u32 s0, s63, s0
	v_cmp_eq_u32_e64 s[14:15], 0, v119
	s_addc_u32 s1, s64, s1
	s_and_saveexec_b64 s[22:23], s[14:15]
	s_cbranch_execz .LBB0_657
	v_mov_b32_e32 v141, v2
	v_lshl_add_u64 v[120:121], s[24:25], 0, v[140:141]
	global_load_dword v119, v[120:121], off
	s_waitcnt lgkmcnt(0)
	v_add_f32_e32 v117, v117, v118
	s_waitcnt vmcnt(0)
	v_add_f32_e32 v117, v117, v119
	v_fmamk_f32 v117, v117, 0x3c2aaaab, v231
	v_cmp_gt_f32_e32 vcc, s11, v117
	v_mul_f32_e32 v118, 0x4b800000, v117
	s_nop 0
	v_cndmask_b32_e32 v117, v117, v118, vcc
	v_rsq_f32_e32 v117, v117
	s_nop 0
	v_mul_f32_e32 v118, 0x45800000, v117
	v_cndmask_b32_e32 v117, v117, v118, vcc
	v_mad_u64_u32 v[118:119], s[24:25], v143, 48, s[0:1]
	v_mov_b32_e32 v120, v119
	v_mad_u64_u32 v[120:121], s[24:25], v142, 48, v[120:121]
	v_mov_b32_e32 v119, v120
	global_store_dword v[118:119], v117, off

.LBB0_2203:
	s_and_b64 vcc, exec, s[16:17]
	s_cbranch_vccnz .LBB0_2233
	v_bfe_i32 v5, v1, 27, 1
	v_lshlrev_b32_e32 v3, 4, v1
	v_lshrrev_b32_e32 v5, 22, v5
	v_add_u32_e32 v5, v3, v5
	v_and_b32_e32 v5, 0xfffffc00, v5
	v_ashrrev_i32_e32 v4, 31, v1
	v_sub_u32_e32 v5, v3, v5
	v_lshrrev_b32_e32 v4, 26, v4
	s_waitcnt vmcnt(14)
	v_lshrrev_b32_e32 v6, 4, v5
	v_add_u32_e32 v4, v1, v4
	v_bitop3_b32 v6, v6, v5, 32 bitop3:0x6c
	v_ashrrev_i32_e32 v5, 31, v5
	v_ashrrev_i32_e32 v4, 6, v4
	v_lshrrev_b32_e32 v5, 26, v5
	v_lshlrev_b32_e32 v7, 3, v4
	v_add_u32_e32 v5, v6, v5
	v_and_b32_e32 v7, -16, v7
	v_ashrrev_i32_e32 v5, 6, v5
	v_add_u32_e32 v7, v5, v7
	v_mul_i32_i24_e32 v5, 64, v5
	v_lshlrev_b32_e32 v4, 5, v4
	v_sub_u32_e32 v5, v6, v5
	v_and_b32_e32 v4, 32, v4
	v_ashrrev_i16_sdwa v5, v235, sext(v5) dst_sel:DWORD dst_unused:UNUSED_PAD src0_sel:DWORD src1_sel:BYTE_0
	s_movk_i32 s1, 0x120
	v_add_u32_sdwa v4, v4, sext(v5) dst_sel:DWORD dst_unused:UNUSED_PAD src0_sel:DWORD src1_sel:WORD_0
	v_mul_lo_u32 v5, v7, s1
	s_waitcnt vmcnt(7)
	v_add_lshl_u32 v132, v4, v5, 1
	v_lshlrev_b32_e32 v5, 9, v7
	v_add_u32_e32 v3, 0x2000, v3
	v_lshl_add_u32 v134, v4, 1, v5
	v_ashrrev_i32_e32 v4, 31, v3
	v_lshrrev_b32_e32 v4, 22, v4
	v_add_u32_e32 v4, v3, v4
	v_ashrrev_i32_e32 v4, 10, v4
	v_mul_i32_i24_e32 v5, 0x400, v4
	v_sub_u32_e32 v3, v3, v5
	v_lshrrev_b32_e32 v5, 4, v3
	v_bitop3_b32 v3, v5, v3, 32 bitop3:0x6c
	v_ashrrev_i32_e32 v6, 31, v3
	v_lshrrev_b32_e32 v6, 26, v6
	v_add_u32_e32 v6, v3, v6
	s_waitcnt lgkmcnt(0)
	s_add_u32 s47, s24, 0x1d123c00
	v_lshlrev_b32_e32 v5, 3, v4
	v_ashrrev_i32_e32 v7, 6, v6
	v_and_b32_e32 v6, 0xc0, v6
	s_addc_u32 s48, s25, 0
	v_and_b32_e32 v5, -16, v5
	v_lshlrev_b32_e32 v4, 5, v4
	v_sub_u32_e32 v3, v3, v6
	s_add_u32 s49, s24, 0x561dc00
	v_add_u32_e32 v5, v7, v5
	v_and_b32_e32 v4, 32, v4
	v_ashrrev_i16_sdwa v3, v235, sext(v3) dst_sel:DWORD dst_unused:UNUSED_PAD src0_sel:DWORD src1_sel:BYTE_0
	s_addc_u32 s50, s25, 0
	v_add_u32_sdwa v3, v4, sext(v3) dst_sel:DWORD dst_unused:UNUSED_PAD src0_sel:DWORD src1_sel:WORD_0
	v_mul_lo_u32 v4, v5, s1
	s_ashr_i32 s7, s46, 6
	s_ashr_i32 s1, s0, 31
	s_ashr_i32 s6, s46, 8
	s_lshl_b32 s51, s7, 10
	s_lshl_b64 s[8:9], s[0:1], 17
	s_add_u32 s16, s49, s8
	s_addc_u32 s17, s50, s9
	s_add_i32 s52, s51, 0
	s_mov_b64 s[8:9], s[16:17]
	s_add_i32 m0, s52, 0x10000
	s_mul_i32 s18, s14, 0x24000
	s_waitcnt vmcnt(6)
	v_add_lshl_u32 v136, v3, v4, 1
	global_load_lds_dwordx4 v134, s[8:9]
	s_add_i32 m0, s52, 0x12000
	v_lshlrev_b32_e32 v4, 9, v5
	s_mul_hi_i32 s15, s14, 0x24000
	s_add_u32 s20, s47, s18
	v_lshl_add_u32 v138, v3, 1, v4
	s_addc_u32 s21, s48, s15
	global_load_lds_dwordx4 v138, s[8:9]
	s_mov_b64 s[8:9], s[20:21]
	s_mov_b32 m0, s52
	s_add_i32 s53, s52, 0x2000
	s_nop 0
	global_load_lds_dwordx4 v132, s[8:9] nt
	s_mov_b32 m0, s53
	s_nop 0
	global_load_lds_dwordx4 v136, s[8:9] nt
	s_add_u32 s8, s16, 0x10000
	s_addc_u32 s9, s17, 0
	s_add_i32 m0, s52, 0x14000
	s_nop 0
	global_load_lds_dwordx4 v134, s[8:9]
	s_add_i32 m0, s52, 0x16000
	s_nop 0
	global_load_lds_dwordx4 v138, s[8:9]
	s_add_u32 s8, s20, 0x12000
	s_addc_u32 s9, s21, 0
	s_add_i32 s54, s52, 0x4000
	s_mov_b32 m0, s54
	s_add_i32 s55, s52, 0x6000
	s_cmp_lg_u32 s6, 1
	global_load_lds_dwordx4 v132, s[8:9] nt
	s_mov_b32 m0, s55
	s_nop 0
	global_load_lds_dwordx4 v136, s[8:9] nt
	s_cbranch_scc1 .LBB0_2206
	s_barrier

.LBB0_2213:
	s_add_u32 s15, s20, s24
	s_addc_u32 s30, s21, s25
	s_add_u32 s31, s15, 0x100
	s_addc_u32 s38, s30, 0
	s_and_b64 s[28:29], s[26:27], exec
	s_cselect_b32 s41, s9, s38
	s_cselect_b32 s40, s8, s31
	s_add_u32 s24, s16, s24
	s_addc_u32 s25, s17, s25
	s_add_u32 s28, s24, 0x100
	s_addc_u32 s29, s25, 0
	s_add_u32 s24, s40, 0x80
	s_addc_u32 s25, s41, 0
	s_add_i32 s79, 0, 0x10000
	s_and_b64 s[26:27], s[26:27], exec
	s_cselect_b32 s43, s1, s29
	s_cselect_b32 s42, s7, s28
	s_add_u32 s44, s15, 0x12080
	s_addc_u32 s45, s30, 0
	s_add_i32 s84, s79, s51
	s_add_i32 m0, s52, 0xc000
	s_add_i32 s85, s52, 0xe000
	s_add_i32 s83, 0, 0x14000
	s_add_i32 s82, s84, 0x2000
	s_add_u32 s38, s42, 0x10000
	s_addc_u32 s39, s43, 0
	s_add_i32 s80, s83, s51
	s_add_i32 s78, s80, 0x2000
	s_add_i32 s75, 0, 0x18000
	v_add_u32_e32 v152, s79, v1
	s_add_u32 s30, s40, 0x12000
	ds_read_b128 v[140:143], v152
	ds_read_b128 v[144:147], v152 offset:1024
	ds_read_b128 v[148:151], v152 offset:2048
	ds_read_b128 v[152:155], v152 offset:3072
	s_addc_u32 s31, s41, 0
	s_add_i32 s73, 0, 0x1c000
	s_add_u32 s28, s42, 0x80
	s_addc_u32 s29, s43, 0
	s_add_i32 s74, s75, s51
	s_add_i32 s15, s74, 0x2000
	s_add_u32 s26, s42, 0x10080
	s_addc_u32 s27, s43, 0
	s_add_i32 s81, s73, s51
	s_add_i32 s79, s81, 0x2000
	ds_read_b128 v[156:159], v3
	ds_read_b128 v[160:163], v3 offset:1024
	ds_read_b128 v[164:167], v3 offset:2048
	ds_read_b128 v[168:171], v3 offset:3072
	ds_read_b128 v[172:175], v3 offset:4096
	ds_read_b128 v[176:179], v3 offset:5120
	ds_read_b128 v[180:183], v3 offset:6144
	ds_read_b128 v[184:187], v3 offset:7168
	s_nop 0
	global_load_lds_dwordx4 v132, s[44:45] nt
	s_mov_b32 m0, s85
	s_nop 0
	global_load_lds_dwordx4 v136, s[44:45] nt
	s_waitcnt lgkmcnt(8)
	s_barrier
	s_waitcnt lgkmcnt(0)
	s_setprio 1
	s_waitcnt lgkmcnt(0)
	v_mfma_f32_16x16x32_bf16 v[128:131], v[140:143], v[156:159], v[128:131]
	v_mfma_f32_16x16x32_bf16 v[124:127], v[148:151], v[156:159], v[124:127]
	v_mfma_f32_16x16x32_bf16 v[112:115], v[140:143], v[164:167], v[112:115]
	v_mfma_f32_16x16x32_bf16 v[108:111], v[148:151], v[164:167], v[108:111]
	v_mfma_f32_16x16x32_bf16 v[96:99], v[140:143], v[172:175], v[96:99]
	v_mfma_f32_16x16x32_bf16 v[92:95], v[148:151], v[172:175], v[92:95]
	v_mfma_f32_16x16x32_bf16 v[80:83], v[140:143], v[180:183], v[80:83]
	v_mfma_f32_16x16x32_bf16 v[76:79], v[148:151], v[180:183], v[76:79]
	v_mfma_f32_16x16x32_bf16 v[128:131], v[144:147], v[160:163], v[128:131]
	v_mfma_f32_16x16x32_bf16 v[124:127], v[152:155], v[160:163], v[124:127]
	v_mfma_f32_16x16x32_bf16 v[112:115], v[144:147], v[168:171], v[112:115]
	v_mfma_f32_16x16x32_bf16 v[108:111], v[152:155], v[168:171], v[108:111]
	v_mfma_f32_16x16x32_bf16 v[96:99], v[144:147], v[176:179], v[96:99]
	v_mfma_f32_16x16x32_bf16 v[92:95], v[152:155], v[176:179], v[92:95]
	v_mfma_f32_16x16x32_bf16 v[80:83], v[144:147], v[184:187], v[80:83]
	v_mfma_f32_16x16x32_bf16 v[76:79], v[152:155], v[184:187], v[76:79]
	s_setprio 0
	s_barrier
	v_add_u32_e32 v214, s83, v1
	s_mov_b32 m0, s84
	ds_read_b128 v[188:191], v214
	ds_read_b128 v[192:195], v214 offset:1024
	ds_read_b128 v[210:213], v214 offset:2048
	ds_read_b128 v[214:217], v214 offset:3072
	s_nop 0
	global_load_lds_dwordx4 v134, s[42:43]
	s_mov_b32 m0, s82
	s_nop 0
	global_load_lds_dwordx4 v138, s[42:43]
	s_barrier
	s_waitcnt lgkmcnt(0)
	s_setprio 1
	s_waitcnt lgkmcnt(0)
	v_mfma_f32_16x16x32_bf16 v[120:123], v[188:191], v[156:159], v[120:123]
	v_mfma_f32_16x16x32_bf16 v[116:119], v[210:213], v[156:159], v[116:119]
	v_mfma_f32_16x16x32_bf16 v[104:107], v[188:191], v[164:167], v[104:107]
	v_mfma_f32_16x16x32_bf16 v[100:103], v[210:213], v[164:167], v[100:103]
	v_mfma_f32_16x16x32_bf16 v[88:91], v[188:191], v[172:175], v[88:91]
	v_mfma_f32_16x16x32_bf16 v[84:87], v[210:213], v[172:175], v[84:87]
	v_mfma_f32_16x16x32_bf16 v[72:75], v[188:191], v[180:183], v[72:75]
	v_mfma_f32_16x16x32_bf16 v[68:71], v[210:213], v[180:183], v[68:71]
	v_mfma_f32_16x16x32_bf16 v[120:123], v[192:195], v[160:163], v[120:123]
	v_mfma_f32_16x16x32_bf16 v[116:119], v[214:217], v[160:163], v[116:119]
	v_mfma_f32_16x16x32_bf16 v[104:107], v[192:195], v[168:171], v[104:107]
	v_mfma_f32_16x16x32_bf16 v[100:103], v[214:217], v[168:171], v[100:103]
	v_mfma_f32_16x16x32_bf16 v[88:91], v[192:195], v[176:179], v[88:91]
	v_mfma_f32_16x16x32_bf16 v[84:87], v[214:217], v[176:179], v[84:87]
	v_mfma_f32_16x16x32_bf16 v[72:75], v[192:195], v[184:187], v[72:75]
	v_mfma_f32_16x16x32_bf16 v[68:71], v[214:217], v[184:187], v[68:71]
	s_setprio 0
	s_mov_b32 m0, s52
	s_barrier
	ds_read_b128 v[156:159], v3 offset:16384
	ds_read_b128 v[160:163], v3 offset:17408
	ds_read_b128 v[164:167], v3 offset:18432
	ds_read_b128 v[168:171], v3 offset:19456
	ds_read_b128 v[172:175], v3 offset:20480
	ds_read_b128 v[176:179], v3 offset:21504
	ds_read_b128 v[180:183], v3 offset:22528
	ds_read_b128 v[184:187], v3 offset:23552
	s_nop 0
	global_load_lds_dwordx4 v132, s[40:41] nt
	s_mov_b32 m0, s53
	s_nop 0
	global_load_lds_dwordx4 v136, s[40:41] nt
	s_barrier
	s_waitcnt lgkmcnt(0)
	s_setprio 1
	s_waitcnt lgkmcnt(0)
	v_mfma_f32_16x16x32_bf16 v[64:67], v[140:143], v[156:159], v[64:67]
	v_mfma_f32_16x16x32_bf16 v[60:63], v[148:151], v[156:159], v[60:63]
	v_mfma_f32_16x16x32_bf16 v[48:51], v[140:143], v[164:167], v[48:51]
	v_mfma_f32_16x16x32_bf16 v[44:47], v[148:151], v[164:167], v[44:47]
	v_mfma_f32_16x16x32_bf16 v[32:35], v[140:143], v[172:175], v[32:35]
	v_mfma_f32_16x16x32_bf16 v[28:31], v[148:151], v[172:175], v[28:31]
	v_mfma_f32_16x16x32_bf16 v[16:19], v[140:143], v[180:183], v[16:19]
	v_mfma_f32_16x16x32_bf16 v[12:15], v[148:151], v[180:183], v[12:15]
	v_mfma_f32_16x16x32_bf16 v[64:67], v[144:147], v[160:163], v[64:67]
	v_mfma_f32_16x16x32_bf16 v[60:63], v[152:155], v[160:163], v[60:63]
	v_mfma_f32_16x16x32_bf16 v[48:51], v[144:147], v[168:171], v[48:51]
	v_mfma_f32_16x16x32_bf16 v[44:47], v[152:155], v[168:171], v[44:47]
	v_mfma_f32_16x16x32_bf16 v[32:35], v[144:147], v[176:179], v[32:35]
	v_mfma_f32_16x16x32_bf16 v[28:31], v[152:155], v[176:179], v[28:31]
	v_mfma_f32_16x16x32_bf16 v[16:19], v[144:147], v[184:187], v[16:19]
	v_mfma_f32_16x16x32_bf16 v[12:15], v[152:155], v[184:187], v[12:15]
	s_setprio 0
	s_barrier
	s_mov_b32 m0, s80
	s_nop 0
	global_load_lds_dwordx4 v134, s[38:39]
	s_mov_b32 m0, s78
	s_nop 0
	global_load_lds_dwordx4 v138, s[38:39]
	s_waitcnt vmcnt(6)
	s_barrier
	s_setprio 1
	v_mfma_f32_16x16x32_bf16 v[56:59], v[188:191], v[156:159], v[56:59]
	v_mfma_f32_16x16x32_bf16 v[52:55], v[210:213], v[156:159], v[52:55]
	v_mfma_f32_16x16x32_bf16 v[40:43], v[188:191], v[164:167], v[40:43]
	v_mfma_f32_16x16x32_bf16 v[36:39], v[210:213], v[164:167], v[36:39]
	v_mfma_f32_16x16x32_bf16 v[24:27], v[188:191], v[172:175], v[24:27]
	v_mfma_f32_16x16x32_bf16 v[20:23], v[210:213], v[172:175], v[20:23]
	v_mfma_f32_16x16x32_bf16 v[8:11], v[188:191], v[180:183], v[8:11]
	v_mfma_f32_16x16x32_bf16 v[4:7], v[210:213], v[180:183], v[4:7]
	v_mfma_f32_16x16x32_bf16 v[56:59], v[192:195], v[160:163], v[56:59]
	v_mfma_f32_16x16x32_bf16 v[52:55], v[214:217], v[160:163], v[52:55]
	v_mfma_f32_16x16x32_bf16 v[40:43], v[192:195], v[168:171], v[40:43]
	v_mfma_f32_16x16x32_bf16 v[36:39], v[214:217], v[168:171], v[36:39]
	v_mfma_f32_16x16x32_bf16 v[24:27], v[192:195], v[176:179], v[24:27]
	v_mfma_f32_16x16x32_bf16 v[20:23], v[214:217], v[176:179], v[20:23]
	v_mfma_f32_16x16x32_bf16 v[8:11], v[192:195], v[184:187], v[8:11]
	v_mfma_f32_16x16x32_bf16 v[4:7], v[214:217], v[184:187], v[4:7]
	s_setprio 0
	v_add_u32_e32 v152, s75, v1
	s_barrier
	ds_read_b128 v[140:143], v152
	ds_read_b128 v[144:147], v152 offset:1024
	ds_read_b128 v[148:151], v152 offset:2048
	ds_read_b128 v[152:155], v152 offset:3072
	s_mov_b32 m0, s54
	ds_read_b128 v[156:159], v3 offset:32768
	ds_read_b128 v[160:163], v3 offset:33792
	ds_read_b128 v[164:167], v3 offset:34816
	ds_read_b128 v[168:171], v3 offset:35840
	ds_read_b128 v[172:175], v3 offset:36864
	ds_read_b128 v[176:179], v3 offset:37888
	ds_read_b128 v[180:183], v3 offset:38912
	ds_read_b128 v[184:187], v3 offset:39936
	s_nop 0
	global_load_lds_dwordx4 v132, s[30:31] nt
	s_mov_b32 m0, s55
	s_nop 0
	global_load_lds_dwordx4 v136, s[30:31] nt
	s_waitcnt lgkmcnt(8)
	s_barrier
	s_waitcnt lgkmcnt(0)
	s_setprio 1
	s_waitcnt lgkmcnt(0)
	v_mfma_f32_16x16x32_bf16 v[128:131], v[140:143], v[156:159], v[128:131]
	v_mfma_f32_16x16x32_bf16 v[124:127], v[148:151], v[156:159], v[124:127]
	v_mfma_f32_16x16x32_bf16 v[112:115], v[140:143], v[164:167], v[112:115]
	v_mfma_f32_16x16x32_bf16 v[108:111], v[148:151], v[164:167], v[108:111]
	v_mfma_f32_16x16x32_bf16 v[96:99], v[140:143], v[172:175], v[96:99]
	v_mfma_f32_16x16x32_bf16 v[92:95], v[148:151], v[172:175], v[92:95]
	v_mfma_f32_16x16x32_bf16 v[80:83], v[140:143], v[180:183], v[80:83]
	v_mfma_f32_16x16x32_bf16 v[76:79], v[148:151], v[180:183], v[76:79]
	v_mfma_f32_16x16x32_bf16 v[128:131], v[144:147], v[160:163], v[128:131]
	v_mfma_f32_16x16x32_bf16 v[124:127], v[152:155], v[160:163], v[124:127]
	v_mfma_f32_16x16x32_bf16 v[112:115], v[144:147], v[168:171], v[112:115]
	v_mfma_f32_16x16x32_bf16 v[108:111], v[152:155], v[168:171], v[108:111]
	v_mfma_f32_16x16x32_bf16 v[96:99], v[144:147], v[176:179], v[96:99]
	v_mfma_f32_16x16x32_bf16 v[92:95], v[152:155], v[176:179], v[92:95]
	v_mfma_f32_16x16x32_bf16 v[80:83], v[144:147], v[184:187], v[80:83]
	v_mfma_f32_16x16x32_bf16 v[76:79], v[152:155], v[184:187], v[76:79]
	s_setprio 0
	s_barrier
	v_add_u32_e32 v214, s73, v1
	s_mov_b32 m0, s74
	ds_read_b128 v[188:191], v214
	ds_read_b128 v[192:195], v214 offset:1024
	ds_read_b128 v[210:213], v214 offset:2048
	ds_read_b128 v[214:217], v214 offset:3072
	s_nop 0
	global_load_lds_dwordx4 v134, s[28:29]
	s_mov_b32 m0, s15
	s_nop 0
	global_load_lds_dwordx4 v138, s[28:29]
	s_barrier
	s_waitcnt lgkmcnt(0)
	s_setprio 1
	s_waitcnt lgkmcnt(0)
	v_mfma_f32_16x16x32_bf16 v[120:123], v[188:191], v[156:159], v[120:123]
	v_mfma_f32_16x16x32_bf16 v[116:119], v[210:213], v[156:159], v[116:119]
	v_mfma_f32_16x16x32_bf16 v[104:107], v[188:191], v[164:167], v[104:107]
	v_mfma_f32_16x16x32_bf16 v[100:103], v[210:213], v[164:167], v[100:103]
	v_mfma_f32_16x16x32_bf16 v[88:91], v[188:191], v[172:175], v[88:91]
	v_mfma_f32_16x16x32_bf16 v[84:87], v[210:213], v[172:175], v[84:87]
	v_mfma_f32_16x16x32_bf16 v[72:75], v[188:191], v[180:183], v[72:75]
	v_mfma_f32_16x16x32_bf16 v[68:71], v[210:213], v[180:183], v[68:71]
	v_mfma_f32_16x16x32_bf16 v[120:123], v[192:195], v[160:163], v[120:123]
	v_mfma_f32_16x16x32_bf16 v[116:119], v[214:217], v[160:163], v[116:119]
	v_mfma_f32_16x16x32_bf16 v[104:107], v[192:195], v[168:171], v[104:107]
	v_mfma_f32_16x16x32_bf16 v[100:103], v[214:217], v[168:171], v[100:103]
	v_mfma_f32_16x16x32_bf16 v[88:91], v[192:195], v[176:179], v[88:91]
	v_mfma_f32_16x16x32_bf16 v[84:87], v[214:217], v[176:179], v[84:87]
	v_mfma_f32_16x16x32_bf16 v[72:75], v[192:195], v[184:187], v[72:75]
	v_mfma_f32_16x16x32_bf16 v[68:71], v[214:217], v[184:187], v[68:71]
	s_setprio 0
	s_mov_b32 m0, s64
	s_barrier
	ds_read_b128 v[156:159], v3 offset:49152
	ds_read_b128 v[160:163], v3 offset:50176
	ds_read_b128 v[164:167], v3 offset:51200
	ds_read_b128 v[168:171], v3 offset:52224
	ds_read_b128 v[172:175], v3 offset:53248
	ds_read_b128 v[176:179], v3 offset:54272
	ds_read_b128 v[180:183], v3 offset:55296
	ds_read_b128 v[184:187], v3 offset:56320
	s_nop 0
	global_load_lds_dwordx4 v132, s[24:25] nt
	s_mov_b32 m0, s65
	s_nop 0
	global_load_lds_dwordx4 v136, s[24:25] nt
	s_barrier
	s_waitcnt lgkmcnt(0)
	s_setprio 1
	s_waitcnt lgkmcnt(0)
	v_mfma_f32_16x16x32_bf16 v[64:67], v[140:143], v[156:159], v[64:67]
	v_mfma_f32_16x16x32_bf16 v[60:63], v[148:151], v[156:159], v[60:63]
	v_mfma_f32_16x16x32_bf16 v[48:51], v[140:143], v[164:167], v[48:51]
	v_mfma_f32_16x16x32_bf16 v[44:47], v[148:151], v[164:167], v[44:47]
	v_mfma_f32_16x16x32_bf16 v[32:35], v[140:143], v[172:175], v[32:35]
	v_mfma_f32_16x16x32_bf16 v[28:31], v[148:151], v[172:175], v[28:31]
	v_mfma_f32_16x16x32_bf16 v[16:19], v[140:143], v[180:183], v[16:19]
	v_mfma_f32_16x16x32_bf16 v[12:15], v[148:151], v[180:183], v[12:15]
	v_mfma_f32_16x16x32_bf16 v[64:67], v[144:147], v[160:163], v[64:67]
	v_mfma_f32_16x16x32_bf16 v[60:63], v[152:155], v[160:163], v[60:63]
	v_mfma_f32_16x16x32_bf16 v[48:51], v[144:147], v[168:171], v[48:51]
	v_mfma_f32_16x16x32_bf16 v[44:47], v[152:155], v[168:171], v[44:47]
	v_mfma_f32_16x16x32_bf16 v[32:35], v[144:147], v[176:179], v[32:35]
	v_mfma_f32_16x16x32_bf16 v[28:31], v[152:155], v[176:179], v[28:31]
	v_mfma_f32_16x16x32_bf16 v[16:19], v[144:147], v[184:187], v[16:19]
	v_mfma_f32_16x16x32_bf16 v[12:15], v[152:155], v[184:187], v[12:15]
	s_setprio 0
	s_barrier
	s_mov_b32 m0, s81
	s_nop 0
	global_load_lds_dwordx4 v134, s[26:27]
	s_mov_b32 m0, s79
	s_nop 0
	global_load_lds_dwordx4 v138, s[26:27]
	s_waitcnt vmcnt(6)
	s_barrier
	s_setprio 1
	v_mfma_f32_16x16x32_bf16 v[56:59], v[188:191], v[156:159], v[56:59]
	v_mfma_f32_16x16x32_bf16 v[52:55], v[210:213], v[156:159], v[52:55]
	v_mfma_f32_16x16x32_bf16 v[40:43], v[188:191], v[164:167], v[40:43]
	v_mfma_f32_16x16x32_bf16 v[36:39], v[210:213], v[164:167], v[36:39]
	v_mfma_f32_16x16x32_bf16 v[24:27], v[188:191], v[172:175], v[24:27]
	v_mfma_f32_16x16x32_bf16 v[20:23], v[210:213], v[172:175], v[20:23]
	v_mfma_f32_16x16x32_bf16 v[8:11], v[188:191], v[180:183], v[8:11]
	v_mfma_f32_16x16x32_bf16 v[4:7], v[210:213], v[180:183], v[4:7]
	v_mfma_f32_16x16x32_bf16 v[56:59], v[192:195], v[160:163], v[56:59]
	v_mfma_f32_16x16x32_bf16 v[52:55], v[214:217], v[160:163], v[52:55]
	v_mfma_f32_16x16x32_bf16 v[40:43], v[192:195], v[168:171], v[40:43]
	v_mfma_f32_16x16x32_bf16 v[36:39], v[214:217], v[168:171], v[36:39]
	v_mfma_f32_16x16x32_bf16 v[24:27], v[192:195], v[176:179], v[24:27]
	v_mfma_f32_16x16x32_bf16 v[20:23], v[214:217], v[176:179], v[20:23]
	v_mfma_f32_16x16x32_bf16 v[8:11], v[192:195], v[184:187], v[8:11]
	v_mfma_f32_16x16x32_bf16 v[4:7], v[214:217], v[184:187], v[4:7]
	s_setprio 0
	s_andn2_b64 vcc, exec, s[22:23]
	s_mov_b64 s[26:27], -1
	s_mov_b64 s[22:23], 0
	s_mov_b64 s[24:25], 0x100
	s_barrier
	s_cbranch_vccz .LBB0_2213
	v_mov_b32_e32 v141, v0
	s_ashr_i32 s15, s14, 31
	v_readfirstlane_b32 s1, v141
	s_bfe_u32 s7, s1, 0x20006
	s_ashr_i32 s1, s1, 2
	s_and_b32 s16, s1, 0xffffffc0
	s_ashr_i32 s17, s16, 31
	s_lshl_b64 s[20:21], s[14:15], 10
	s_add_u32 s1, s56, s20
	s_addc_u32 s22, s57, s21
	s_lshl_b64 s[20:21], s[16:17], 2
	v_and_b32_e32 v142, 15, v141
	s_add_u32 s20, s1, s20
	s_addc_u32 s21, s22, s21
	v_lshlrev_b32_e32 v140, 2, v142
	s_min_u32 s100, s72, 0x7ff
	s_lshl_b32 s100, s100, 10
	v_and_b32_e32 v210, 7, v0
	v_lshlrev_b32_e32 v210, 7, v210
	v_add_u32_e32 v210, s100, v210
	global_load_dword v211, v210, s[56:57]
	global_load_dword v150, v140, s[20:21] offset:64
	global_load_dword v149, v140, s[20:21] offset:128
	global_load_dword v148, v140, s[20:21] offset:192
	global_load_dword v147, v140, s[20:21] offset:512
	global_load_dword v146, v140, s[20:21] offset:576
	global_load_dword v145, v140, s[20:21] offset:640
	global_load_dword v144, v140, s[20:21] offset:704
	v_mul_f32_e32 v129, v129, v129
	v_mul_f32_e32 v125, v125, v125
	v_mul_f32_e32 v121, v121, v121
	v_mul_f32_e32 v117, v117, v117
	v_fmac_f32_e32 v129, v128, v128
	v_mul_f32_e32 v128, v131, v131
	v_fmac_f32_e32 v125, v124, v124
	v_mul_f32_e32 v124, v127, v127
	v_fmac_f32_e32 v121, v120, v120
	v_mul_f32_e32 v120, v123, v123
	v_fmac_f32_e32 v117, v116, v116
	v_mul_f32_e32 v116, v119, v119
	v_fmac_f32_e32 v128, v130, v130
	v_fmac_f32_e32 v124, v126, v126
	v_fmac_f32_e32 v120, v122, v122
	v_fmac_f32_e32 v116, v118, v118
	v_add_f32_e32 v128, v129, v128
	v_add_f32_e32 v124, v125, v124
	v_add_f32_e32 v120, v121, v120
	v_add_f32_e32 v116, v117, v116
	v_add_f32_e32 v124, v128, v124
	v_add_f32_e32 v116, v120, v116
	v_add_f32_e32 v117, v124, v116
	v_mov_b32_e32 v118, v117
	s_nop 1
	v_permlane16_swap_b32 v118, v117
	v_and_b32_e32 v152, 64, v236
	v_xor_b32_e32 v151, 32, v236
	v_add_u32_e32 v152, 64, v152
	v_cmp_lt_i32_e32 vcc, v151, v152
	s_lshl_b32 s0, s0, 2
	s_or_b32 s0, s7, s0
	v_cndmask_b32_e32 v116, v236, v151, vcc
	s_lshl_b64 s[14:15], s[14:15], 8
	v_lshlrev_b32_e32 v116, 2, v116
	s_waitcnt lgkmcnt(0)
	v_add_f32_e32 v117, v117, v118
	s_add_u32 s1, s14, s16
	v_mov_b32_e32 v118, v117
	s_nop 1
	v_permlane32_swap_b32 v118, v117
	s_addc_u32 s7, s15, s17
	v_or_b32_e32 v143, s1, v142
	s_ashr_i32 s1, s0, 31
	s_lshl_b64 s[0:1], s[0:1], 2
	v_and_b32_e32 v119, 48, v141
	s_add_u32 s0, s62, s0
	v_mov_b32_e32 v142, s7
	v_cmp_eq_u32_e64 s[16:17], 0, v119
	s_addc_u32 s1, s63, s1
	s_and_saveexec_b64 s[14:15], s[16:17]
	s_cbranch_execz .LBB0_2216
	v_mov_b32_e32 v141, v2
	v_lshl_add_u64 v[120:121], s[20:21], 0, v[140:141]
	global_load_dword v119, v[120:121], off
	s_waitcnt lgkmcnt(0)
	v_add_f32_e32 v117, v117, v118
	s_waitcnt vmcnt(0)
	v_add_f32_e32 v117, v117, v119
	v_fmamk_f32 v117, v117, 0x3c2aaaab, v231
	v_cmp_gt_f32_e32 vcc, s11, v117
	v_mul_f32_e32 v118, 0x4b800000, v117
	s_nop 0
	v_cndmask_b32_e32 v117, v117, v118, vcc
	v_rsq_f32_e32 v117, v117
	s_nop 0
	v_mul_f32_e32 v118, 0x45800000, v117
	v_cndmask_b32_e32 v117, v117, v118, vcc
	v_mad_u64_u32 v[118:119], s[20:21], v143, 48, s[0:1]
	v_mov_b32_e32 v120, v119
	v_mad_u64_u32 v[120:121], s[20:21], v142, 48, v[120:121]
	v_mov_b32_e32 v119, v120
	global_store_dword v[118:119], v117, off

.LBB0_3041:
	v_mov_b32_e32 v1, v0
	s_movk_i32 s9, 0x120
	v_bfe_i32 v5, v1, 27, 1
	v_lshlrev_b32_e32 v3, 4, v1
	v_lshrrev_b32_e32 v5, 22, v5
	v_add_u32_e32 v5, v3, v5
	v_and_b32_e32 v5, 0xfffffc00, v5
	v_ashrrev_i32_e32 v4, 31, v1
	v_sub_u32_e32 v5, v3, v5
	v_lshrrev_b32_e32 v4, 26, v4
	v_lshrrev_b32_e32 v6, 4, v5
	v_add_u32_e32 v4, v1, v4
	v_bitop3_b32 v6, v6, v5, 32 bitop3:0x6c
	v_ashrrev_i32_e32 v5, 31, v5
	v_ashrrev_i32_e32 v4, 6, v4
	v_lshrrev_b32_e32 v5, 26, v5
	v_lshlrev_b32_e32 v7, 3, v4
	v_add_u32_e32 v5, v6, v5
	v_and_b32_e32 v7, -16, v7
	v_ashrrev_i32_e32 v5, 6, v5
	v_add_u32_e32 v7, v5, v7
	v_mul_i32_i24_e32 v5, 64, v5
	v_lshlrev_b32_e32 v4, 5, v4
	v_sub_u32_e32 v5, v6, v5
	v_and_b32_e32 v4, 32, v4
	v_ashrrev_i16_sdwa v5, v235, sext(v5) dst_sel:DWORD dst_unused:UNUSED_PAD src0_sel:DWORD src1_sel:BYTE_0
	v_add_u32_sdwa v4, v4, sext(v5) dst_sel:DWORD dst_unused:UNUSED_PAD src0_sel:DWORD src1_sel:WORD_0
	v_mul_lo_u32 v5, v7, s9
	v_add_lshl_u32 v132, v4, v5, 1
	v_lshlrev_b32_e32 v5, 9, v7
	v_add_u32_e32 v3, 0x2000, v3
	v_lshl_add_u32 v134, v4, 1, v5
	v_ashrrev_i32_e32 v4, 31, v3
	v_lshrrev_b32_e32 v4, 22, v4
	v_add_u32_e32 v4, v3, v4
	v_ashrrev_i32_e32 v4, 10, v4
	v_mul_i32_i24_e32 v5, 0x400, v4
	v_sub_u32_e32 v3, v3, v5
	v_lshrrev_b32_e32 v5, 4, v3
	s_add_u32 s52, s38, 0x1d123c00
	v_bitop3_b32 v3, v5, v3, 32 bitop3:0x6c
	s_addc_u32 s53, s39, 0
	v_ashrrev_i32_e32 v6, 31, v3
	s_add_u32 s54, s38, 0x561dc00
	v_lshrrev_b32_e32 v6, 26, v6
	s_addc_u32 s55, s39, 0
	v_add_u32_e32 v6, v3, v6
	s_add_i32 s62, s8, s0
	v_lshlrev_b32_e32 v5, 3, v4
	v_ashrrev_i32_e32 v7, 6, v6
	v_and_b32_e32 v6, 0xc0, v6
	s_ashr_i32 s0, s62, 31
	v_and_b32_e32 v5, -16, v5
	v_lshlrev_b32_e32 v4, 5, v4
	v_sub_u32_e32 v3, v3, v6
	s_lshr_b32 s0, s0, 29
	v_readfirstlane_b32 s56, v1
	v_add_u32_e32 v5, v7, v5
	v_and_b32_e32 v4, 32, v4
	v_ashrrev_i16_sdwa v3, v235, sext(v3) dst_sel:DWORD dst_unused:UNUSED_PAD src0_sel:DWORD src1_sel:BYTE_0
	s_add_i32 s0, s62, s0
	v_add_u32_sdwa v3, v4, sext(v3) dst_sel:DWORD dst_unused:UNUSED_PAD src0_sel:DWORD src1_sel:WORD_0
	v_mul_lo_u32 v4, v5, s9
	s_ashr_i32 s9, s56, 6
	s_ashr_i32 s8, s0, 3
	s_and_b32 s0, s0, -8
	s_ashr_i32 s1, s56, 8
	s_lshl_b32 s57, s9, 10
	s_sub_i32 s0, s62, s0
	s_cmp_lt_i32 s0, 0
	s_movk_i32 s14, 0x181
	s_cselect_b32 s14, s14, 0x180
	s_mul_i32 s0, s14, s0
	s_add_i32 s0, s0, s8
	s_mul_hi_i32 s8, s0, 0x2aaaaaab
	s_lshr_b32 s14, s8, 31
	s_ashr_i32 s8, s8, 2
	s_add_i32 s8, s8, s14
	s_lshl_b32 s14, s8, 3
	s_mul_i32 s8, s8, 24
	s_sub_i32 s0, s0, s8
	s_bfe_i32 s8, s0, 0x80000
	s_bfe_u32 s8, s8, 0x3000c
	s_add_i32 s15, s0, s8
	s_bfe_i32 s8, s15, 0x80000
	s_and_b32 s15, s15, 0xf8
	s_sext_i32_i16 s8, s8
	s_sub_i32 s0, s0, s15
	s_lshr_b32 s8, s8, 3
	s_sext_i32_i8 s0, s0
	s_add_i32 s0, s14, s0
	s_bfe_i64 s[14:15], s[8:9], 0x100000
	s_addk_i32 s0, 0x400
	s_lshl_b64 s[14:15], s[14:15], 17
	s_add_u32 s14, s54, s14
	s_addc_u32 s15, s55, s15
	s_add_i32 s63, s57, 0
	s_mov_b64 s[16:17], s[14:15]
	s_add_i32 m0, s63, 0x10000
	s_mul_i32 s19, s0, 0x24000
	v_add_lshl_u32 v136, v3, v4, 1
	global_load_lds_dwordx4 v134, s[16:17]
	s_add_i32 m0, s63, 0x12000
	v_lshlrev_b32_e32 v4, 9, v5
	s_mul_hi_i32 s18, s0, 0x24000
	s_add_u32 s22, s52, s19
	v_lshl_add_u32 v138, v3, 1, v4
	s_addc_u32 s23, s53, s18
	global_load_lds_dwordx4 v138, s[16:17]
	s_mov_b64 s[16:17], s[22:23]
	s_mov_b32 m0, s63
	s_add_i32 s64, s63, 0x2000
	s_nop 0
	global_load_lds_dwordx4 v132, s[16:17] nt
	s_mov_b32 m0, s64
	s_nop 0
	global_load_lds_dwordx4 v136, s[16:17] nt
	s_add_u32 s16, s14, 0x10000
	s_addc_u32 s17, s15, 0
	s_add_i32 m0, s63, 0x14000
	s_nop 0
	global_load_lds_dwordx4 v134, s[16:17]
	s_add_i32 m0, s63, 0x16000
	s_nop 0
	global_load_lds_dwordx4 v138, s[16:17]
	s_add_u32 s16, s22, 0x12000
	s_addc_u32 s17, s23, 0
	s_add_i32 s65, s63, 0x4000
	s_mov_b32 m0, s65
	s_add_i32 s67, s63, 0x6000
	s_cmp_lg_u32 s1, 1
	global_load_lds_dwordx4 v132, s[16:17] nt
	s_mov_b32 m0, s67
	s_nop 0
	global_load_lds_dwordx4 v136, s[16:17] nt
	s_cbranch_scc1 .LBB0_3043
	s_barrier

.LBB0_3050:
	s_add_u32 s30, s22, s24
	s_addc_u32 s31, s23, s25
	s_add_u32 s40, s30, 0x100
	s_addc_u32 s41, s31, 0
	s_and_b64 s[28:29], s[26:27], exec
	s_cselect_b32 s43, s19, s41
	s_cselect_b32 s42, s18, s40
	s_add_u32 s24, s14, s24
	s_addc_u32 s25, s15, s25
	s_add_u32 s28, s24, 0x100
	s_addc_u32 s29, s25, 0
	s_add_u32 s24, s42, 0x80
	s_addc_u32 s25, s43, 0
	s_and_b64 s[26:27], s[26:27], exec
	s_cselect_b32 s45, s1, s29
	s_cselect_b32 s44, s9, s28
	s_add_u32 s46, s30, 0x12080
	s_addc_u32 s47, s31, 0
	s_add_i32 s95, s84, s57
	s_add_i32 m0, s63, 0xc000
	s_add_i32 s97, s63, 0xe000
	s_add_i32 s94, s95, 0x2000
	s_add_u32 s40, s44, 0x10000
	s_addc_u32 s41, s45, 0
	s_add_i32 s93, s85, s57
	s_add_i32 s92, s93, 0x2000
	v_add_u32_e32 v152, s84, v1
	s_add_u32 s30, s42, 0x12000
	ds_read_b128 v[140:143], v152
	ds_read_b128 v[144:147], v152 offset:1024
	ds_read_b128 v[148:151], v152 offset:2048
	ds_read_b128 v[152:155], v152 offset:3072
	s_addc_u32 s31, s43, 0
	s_add_u32 s28, s44, 0x80
	s_addc_u32 s29, s45, 0
	s_add_i32 s91, s88, s57
	s_add_i32 s90, s91, 0x2000
	s_add_u32 s26, s44, 0x10080
	s_addc_u32 s27, s45, 0
	s_add_i32 s87, s89, s57
	s_add_i32 s86, s87, 0x2000
	ds_read_b128 v[156:159], v3
	ds_read_b128 v[160:163], v3 offset:1024
	ds_read_b128 v[164:167], v3 offset:2048
	ds_read_b128 v[168:171], v3 offset:3072
	ds_read_b128 v[172:175], v3 offset:4096
	ds_read_b128 v[176:179], v3 offset:5120
	ds_read_b128 v[180:183], v3 offset:6144
	ds_read_b128 v[184:187], v3 offset:7168
	s_nop 0
	global_load_lds_dwordx4 v132, s[46:47] nt
	s_mov_b32 m0, s97
	s_nop 0
	global_load_lds_dwordx4 v136, s[46:47] nt
	s_waitcnt lgkmcnt(8)
	s_barrier
	s_waitcnt lgkmcnt(0)
	s_setprio 1
	s_waitcnt lgkmcnt(0)
	v_mfma_f32_16x16x32_bf16 v[128:131], v[140:143], v[156:159], v[128:131]
	v_mfma_f32_16x16x32_bf16 v[124:127], v[148:151], v[156:159], v[124:127]
	v_mfma_f32_16x16x32_bf16 v[112:115], v[140:143], v[164:167], v[112:115]
	v_mfma_f32_16x16x32_bf16 v[108:111], v[148:151], v[164:167], v[108:111]
	v_mfma_f32_16x16x32_bf16 v[96:99], v[140:143], v[172:175], v[96:99]
	v_mfma_f32_16x16x32_bf16 v[92:95], v[148:151], v[172:175], v[92:95]
	v_mfma_f32_16x16x32_bf16 v[80:83], v[140:143], v[180:183], v[80:83]
	v_mfma_f32_16x16x32_bf16 v[76:79], v[148:151], v[180:183], v[76:79]
	v_mfma_f32_16x16x32_bf16 v[128:131], v[144:147], v[160:163], v[128:131]
	v_mfma_f32_16x16x32_bf16 v[124:127], v[152:155], v[160:163], v[124:127]
	v_mfma_f32_16x16x32_bf16 v[112:115], v[144:147], v[168:171], v[112:115]
	v_mfma_f32_16x16x32_bf16 v[108:111], v[152:155], v[168:171], v[108:111]
	v_mfma_f32_16x16x32_bf16 v[96:99], v[144:147], v[176:179], v[96:99]
	v_mfma_f32_16x16x32_bf16 v[92:95], v[152:155], v[176:179], v[92:95]
	v_mfma_f32_16x16x32_bf16 v[80:83], v[144:147], v[184:187], v[80:83]
	v_mfma_f32_16x16x32_bf16 v[76:79], v[152:155], v[184:187], v[76:79]
	s_setprio 0
	s_barrier
	v_add_u32_e32 v196, s85, v1
	s_mov_b32 m0, s95
	ds_read_b128 v[188:191], v196
	ds_read_b128 v[192:195], v196 offset:1024
	ds_read_b128 v[210:213], v196 offset:2048
	ds_read_b128 v[214:217], v196 offset:3072
	s_nop 0
	global_load_lds_dwordx4 v134, s[44:45]
	s_mov_b32 m0, s94
	s_nop 0
	global_load_lds_dwordx4 v138, s[44:45]
	s_barrier
	s_waitcnt lgkmcnt(0)
	s_setprio 1
	s_waitcnt lgkmcnt(0)
	v_mfma_f32_16x16x32_bf16 v[120:123], v[188:191], v[156:159], v[120:123]
	v_mfma_f32_16x16x32_bf16 v[116:119], v[210:213], v[156:159], v[116:119]
	v_mfma_f32_16x16x32_bf16 v[104:107], v[188:191], v[164:167], v[104:107]
	v_mfma_f32_16x16x32_bf16 v[100:103], v[210:213], v[164:167], v[100:103]
	v_mfma_f32_16x16x32_bf16 v[88:91], v[188:191], v[172:175], v[88:91]
	v_mfma_f32_16x16x32_bf16 v[84:87], v[210:213], v[172:175], v[84:87]
	v_mfma_f32_16x16x32_bf16 v[72:75], v[188:191], v[180:183], v[72:75]
	v_mfma_f32_16x16x32_bf16 v[68:71], v[210:213], v[180:183], v[68:71]
	v_mfma_f32_16x16x32_bf16 v[120:123], v[192:195], v[160:163], v[120:123]
	v_mfma_f32_16x16x32_bf16 v[116:119], v[214:217], v[160:163], v[116:119]
	v_mfma_f32_16x16x32_bf16 v[104:107], v[192:195], v[168:171], v[104:107]
	v_mfma_f32_16x16x32_bf16 v[100:103], v[214:217], v[168:171], v[100:103]
	v_mfma_f32_16x16x32_bf16 v[88:91], v[192:195], v[176:179], v[88:91]
	v_mfma_f32_16x16x32_bf16 v[84:87], v[214:217], v[176:179], v[84:87]
	v_mfma_f32_16x16x32_bf16 v[72:75], v[192:195], v[184:187], v[72:75]
	v_mfma_f32_16x16x32_bf16 v[68:71], v[214:217], v[184:187], v[68:71]
	s_setprio 0
	s_mov_b32 m0, s63
	s_barrier
	ds_read_b128 v[156:159], v3 offset:16384
	ds_read_b128 v[160:163], v3 offset:17408
	ds_read_b128 v[164:167], v3 offset:18432
	ds_read_b128 v[168:171], v3 offset:19456
	ds_read_b128 v[172:175], v3 offset:20480
	ds_read_b128 v[176:179], v3 offset:21504
	ds_read_b128 v[180:183], v3 offset:22528
	ds_read_b128 v[184:187], v3 offset:23552
	s_nop 0
	global_load_lds_dwordx4 v132, s[42:43] nt
	s_mov_b32 m0, s64
	s_nop 0
	global_load_lds_dwordx4 v136, s[42:43] nt
	s_barrier
	s_waitcnt lgkmcnt(0)
	s_setprio 1
	s_waitcnt lgkmcnt(0)
	v_mfma_f32_16x16x32_bf16 v[64:67], v[140:143], v[156:159], v[64:67]
	v_mfma_f32_16x16x32_bf16 v[60:63], v[148:151], v[156:159], v[60:63]
	v_mfma_f32_16x16x32_bf16 v[48:51], v[140:143], v[164:167], v[48:51]
	v_mfma_f32_16x16x32_bf16 v[44:47], v[148:151], v[164:167], v[44:47]
	v_mfma_f32_16x16x32_bf16 v[32:35], v[140:143], v[172:175], v[32:35]
	v_mfma_f32_16x16x32_bf16 v[28:31], v[148:151], v[172:175], v[28:31]
	v_mfma_f32_16x16x32_bf16 v[16:19], v[140:143], v[180:183], v[16:19]
	v_mfma_f32_16x16x32_bf16 v[12:15], v[148:151], v[180:183], v[12:15]
	v_mfma_f32_16x16x32_bf16 v[64:67], v[144:147], v[160:163], v[64:67]
	v_mfma_f32_16x16x32_bf16 v[60:63], v[152:155], v[160:163], v[60:63]
	v_mfma_f32_16x16x32_bf16 v[48:51], v[144:147], v[168:171], v[48:51]
	v_mfma_f32_16x16x32_bf16 v[44:47], v[152:155], v[168:171], v[44:47]
	v_mfma_f32_16x16x32_bf16 v[32:35], v[144:147], v[176:179], v[32:35]
	v_mfma_f32_16x16x32_bf16 v[28:31], v[152:155], v[176:179], v[28:31]
	v_mfma_f32_16x16x32_bf16 v[16:19], v[144:147], v[184:187], v[16:19]
	v_mfma_f32_16x16x32_bf16 v[12:15], v[152:155], v[184:187], v[12:15]
	s_setprio 0
	s_barrier
	s_mov_b32 m0, s93
	s_nop 0
	global_load_lds_dwordx4 v134, s[40:41]
	s_mov_b32 m0, s92
	s_nop 0
	global_load_lds_dwordx4 v138, s[40:41]
	s_waitcnt vmcnt(6)
	s_barrier
	s_setprio 1
	v_mfma_f32_16x16x32_bf16 v[56:59], v[188:191], v[156:159], v[56:59]
	v_mfma_f32_16x16x32_bf16 v[52:55], v[210:213], v[156:159], v[52:55]
	v_mfma_f32_16x16x32_bf16 v[40:43], v[188:191], v[164:167], v[40:43]
	v_mfma_f32_16x16x32_bf16 v[36:39], v[210:213], v[164:167], v[36:39]
	v_mfma_f32_16x16x32_bf16 v[24:27], v[188:191], v[172:175], v[24:27]
	v_mfma_f32_16x16x32_bf16 v[20:23], v[210:213], v[172:175], v[20:23]
	v_mfma_f32_16x16x32_bf16 v[8:11], v[188:191], v[180:183], v[8:11]
	v_mfma_f32_16x16x32_bf16 v[4:7], v[210:213], v[180:183], v[4:7]
	v_mfma_f32_16x16x32_bf16 v[56:59], v[192:195], v[160:163], v[56:59]
	v_mfma_f32_16x16x32_bf16 v[52:55], v[214:217], v[160:163], v[52:55]
	v_mfma_f32_16x16x32_bf16 v[40:43], v[192:195], v[168:171], v[40:43]
	v_mfma_f32_16x16x32_bf16 v[36:39], v[214:217], v[168:171], v[36:39]
	v_mfma_f32_16x16x32_bf16 v[24:27], v[192:195], v[176:179], v[24:27]
	v_mfma_f32_16x16x32_bf16 v[20:23], v[214:217], v[176:179], v[20:23]
	v_mfma_f32_16x16x32_bf16 v[8:11], v[192:195], v[184:187], v[8:11]
	v_mfma_f32_16x16x32_bf16 v[4:7], v[214:217], v[184:187], v[4:7]
	s_setprio 0
	v_add_u32_e32 v152, s88, v1
	s_barrier
	ds_read_b128 v[140:143], v152
	ds_read_b128 v[144:147], v152 offset:1024
	ds_read_b128 v[148:151], v152 offset:2048
	ds_read_b128 v[152:155], v152 offset:3072
	s_mov_b32 m0, s65
	ds_read_b128 v[156:159], v3 offset:32768
	ds_read_b128 v[160:163], v3 offset:33792
	ds_read_b128 v[164:167], v3 offset:34816
	ds_read_b128 v[168:171], v3 offset:35840
	ds_read_b128 v[172:175], v3 offset:36864
	ds_read_b128 v[176:179], v3 offset:37888
	ds_read_b128 v[180:183], v3 offset:38912
	ds_read_b128 v[184:187], v3 offset:39936
	s_nop 0
	global_load_lds_dwordx4 v132, s[30:31] nt
	s_mov_b32 m0, s67
	s_nop 0
	global_load_lds_dwordx4 v136, s[30:31] nt
	s_waitcnt lgkmcnt(8)
	s_barrier
	s_waitcnt lgkmcnt(0)
	s_setprio 1
	s_waitcnt lgkmcnt(0)
	v_mfma_f32_16x16x32_bf16 v[128:131], v[140:143], v[156:159], v[128:131]
	v_mfma_f32_16x16x32_bf16 v[124:127], v[148:151], v[156:159], v[124:127]
	v_mfma_f32_16x16x32_bf16 v[112:115], v[140:143], v[164:167], v[112:115]
	v_mfma_f32_16x16x32_bf16 v[108:111], v[148:151], v[164:167], v[108:111]
	v_mfma_f32_16x16x32_bf16 v[96:99], v[140:143], v[172:175], v[96:99]
	v_mfma_f32_16x16x32_bf16 v[92:95], v[148:151], v[172:175], v[92:95]
	v_mfma_f32_16x16x32_bf16 v[80:83], v[140:143], v[180:183], v[80:83]
	v_mfma_f32_16x16x32_bf16 v[76:79], v[148:151], v[180:183], v[76:79]
	v_mfma_f32_16x16x32_bf16 v[128:131], v[144:147], v[160:163], v[128:131]
	v_mfma_f32_16x16x32_bf16 v[124:127], v[152:155], v[160:163], v[124:127]
	v_mfma_f32_16x16x32_bf16 v[112:115], v[144:147], v[168:171], v[112:115]
	v_mfma_f32_16x16x32_bf16 v[108:111], v[152:155], v[168:171], v[108:111]
	v_mfma_f32_16x16x32_bf16 v[96:99], v[144:147], v[176:179], v[96:99]
	v_mfma_f32_16x16x32_bf16 v[92:95], v[152:155], v[176:179], v[92:95]
	v_mfma_f32_16x16x32_bf16 v[80:83], v[144:147], v[184:187], v[80:83]
	v_mfma_f32_16x16x32_bf16 v[76:79], v[152:155], v[184:187], v[76:79]
	s_setprio 0
	s_barrier
	v_add_u32_e32 v196, s89, v1
	s_mov_b32 m0, s91
	ds_read_b128 v[188:191], v196
	ds_read_b128 v[192:195], v196 offset:1024
	ds_read_b128 v[210:213], v196 offset:2048
	ds_read_b128 v[214:217], v196 offset:3072
	s_nop 0
	global_load_lds_dwordx4 v134, s[28:29]
	s_mov_b32 m0, s90
	s_nop 0
	global_load_lds_dwordx4 v138, s[28:29]
	s_barrier
	s_waitcnt lgkmcnt(0)
	s_setprio 1
	s_waitcnt lgkmcnt(0)
	v_mfma_f32_16x16x32_bf16 v[120:123], v[188:191], v[156:159], v[120:123]
	v_mfma_f32_16x16x32_bf16 v[116:119], v[210:213], v[156:159], v[116:119]
	v_mfma_f32_16x16x32_bf16 v[104:107], v[188:191], v[164:167], v[104:107]
	v_mfma_f32_16x16x32_bf16 v[100:103], v[210:213], v[164:167], v[100:103]
	v_mfma_f32_16x16x32_bf16 v[88:91], v[188:191], v[172:175], v[88:91]
	v_mfma_f32_16x16x32_bf16 v[84:87], v[210:213], v[172:175], v[84:87]
	v_mfma_f32_16x16x32_bf16 v[72:75], v[188:191], v[180:183], v[72:75]
	v_mfma_f32_16x16x32_bf16 v[68:71], v[210:213], v[180:183], v[68:71]
	v_mfma_f32_16x16x32_bf16 v[120:123], v[192:195], v[160:163], v[120:123]
	v_mfma_f32_16x16x32_bf16 v[116:119], v[214:217], v[160:163], v[116:119]
	v_mfma_f32_16x16x32_bf16 v[104:107], v[192:195], v[168:171], v[104:107]
	v_mfma_f32_16x16x32_bf16 v[100:103], v[214:217], v[168:171], v[100:103]
	v_mfma_f32_16x16x32_bf16 v[88:91], v[192:195], v[176:179], v[88:91]
	v_mfma_f32_16x16x32_bf16 v[84:87], v[214:217], v[176:179], v[84:87]
	v_mfma_f32_16x16x32_bf16 v[72:75], v[192:195], v[184:187], v[72:75]
	v_mfma_f32_16x16x32_bf16 v[68:71], v[214:217], v[184:187], v[68:71]
	s_setprio 0
	s_mov_b32 m0, s75
	s_barrier
	ds_read_b128 v[156:159], v3 offset:49152
	ds_read_b128 v[160:163], v3 offset:50176
	ds_read_b128 v[164:167], v3 offset:51200
	ds_read_b128 v[168:171], v3 offset:52224
	ds_read_b128 v[172:175], v3 offset:53248
	ds_read_b128 v[176:179], v3 offset:54272
	ds_read_b128 v[180:183], v3 offset:55296
	ds_read_b128 v[184:187], v3 offset:56320
	s_nop 0
	global_load_lds_dwordx4 v132, s[24:25] nt
	s_mov_b32 m0, s78
	s_nop 0
	global_load_lds_dwordx4 v136, s[24:25] nt
	s_barrier
	s_waitcnt lgkmcnt(0)
	s_setprio 1
	s_waitcnt lgkmcnt(0)
	v_mfma_f32_16x16x32_bf16 v[64:67], v[140:143], v[156:159], v[64:67]
	v_mfma_f32_16x16x32_bf16 v[60:63], v[148:151], v[156:159], v[60:63]
	v_mfma_f32_16x16x32_bf16 v[48:51], v[140:143], v[164:167], v[48:51]
	v_mfma_f32_16x16x32_bf16 v[44:47], v[148:151], v[164:167], v[44:47]
	v_mfma_f32_16x16x32_bf16 v[32:35], v[140:143], v[172:175], v[32:35]
	v_mfma_f32_16x16x32_bf16 v[28:31], v[148:151], v[172:175], v[28:31]
	v_mfma_f32_16x16x32_bf16 v[16:19], v[140:143], v[180:183], v[16:19]
	v_mfma_f32_16x16x32_bf16 v[12:15], v[148:151], v[180:183], v[12:15]
	v_mfma_f32_16x16x32_bf16 v[64:67], v[144:147], v[160:163], v[64:67]
	v_mfma_f32_16x16x32_bf16 v[60:63], v[152:155], v[160:163], v[60:63]
	v_mfma_f32_16x16x32_bf16 v[48:51], v[144:147], v[168:171], v[48:51]
	v_mfma_f32_16x16x32_bf16 v[44:47], v[152:155], v[168:171], v[44:47]
	v_mfma_f32_16x16x32_bf16 v[32:35], v[144:147], v[176:179], v[32:35]
	v_mfma_f32_16x16x32_bf16 v[28:31], v[152:155], v[176:179], v[28:31]
	v_mfma_f32_16x16x32_bf16 v[16:19], v[144:147], v[184:187], v[16:19]
	v_mfma_f32_16x16x32_bf16 v[12:15], v[152:155], v[184:187], v[12:15]
	s_setprio 0
	s_barrier
	s_mov_b32 m0, s87
	s_nop 0
	global_load_lds_dwordx4 v134, s[26:27]
	s_mov_b32 m0, s86
	s_nop 0
	global_load_lds_dwordx4 v138, s[26:27]
	s_waitcnt vmcnt(6)
	s_barrier
	s_setprio 1
	v_mfma_f32_16x16x32_bf16 v[56:59], v[188:191], v[156:159], v[56:59]
	v_mfma_f32_16x16x32_bf16 v[52:55], v[210:213], v[156:159], v[52:55]
	v_mfma_f32_16x16x32_bf16 v[40:43], v[188:191], v[164:167], v[40:43]
	v_mfma_f32_16x16x32_bf16 v[36:39], v[210:213], v[164:167], v[36:39]
	v_mfma_f32_16x16x32_bf16 v[24:27], v[188:191], v[172:175], v[24:27]
	v_mfma_f32_16x16x32_bf16 v[20:23], v[210:213], v[172:175], v[20:23]
	v_mfma_f32_16x16x32_bf16 v[8:11], v[188:191], v[180:183], v[8:11]
	v_mfma_f32_16x16x32_bf16 v[4:7], v[210:213], v[180:183], v[4:7]
	v_mfma_f32_16x16x32_bf16 v[56:59], v[192:195], v[160:163], v[56:59]
	v_mfma_f32_16x16x32_bf16 v[52:55], v[214:217], v[160:163], v[52:55]
	v_mfma_f32_16x16x32_bf16 v[40:43], v[192:195], v[168:171], v[40:43]
	v_mfma_f32_16x16x32_bf16 v[36:39], v[214:217], v[168:171], v[36:39]
	v_mfma_f32_16x16x32_bf16 v[24:27], v[192:195], v[176:179], v[24:27]
	v_mfma_f32_16x16x32_bf16 v[20:23], v[214:217], v[176:179], v[20:23]
	v_mfma_f32_16x16x32_bf16 v[8:11], v[192:195], v[184:187], v[8:11]
	v_mfma_f32_16x16x32_bf16 v[4:7], v[214:217], v[184:187], v[4:7]
	s_setprio 0
	s_andn2_b64 vcc, exec, s[16:17]
	s_mov_b64 s[26:27], -1
	s_mov_b64 s[16:17], 0
	s_mov_b64 s[24:25], 0x100
	s_barrier
	s_cbranch_vccz .LBB0_3050
	v_mov_b32_e32 v141, v0
	s_ashr_i32 s1, s0, 31
	v_readfirstlane_b32 s9, v141
	s_bfe_u32 s24, s9, 0x20006
	s_ashr_i32 s9, s9, 2
	s_and_b32 s14, s9, 0xffffffc0
	s_ashr_i32 s15, s14, 31
	s_lshl_b64 s[16:17], s[0:1], 10
	s_add_u32 s9, s68, s16
	s_addc_u32 s23, s72, s17
	s_lshl_b64 s[16:17], s[14:15], 2
	v_and_b32_e32 v142, 15, v141
	s_add_u32 s22, s9, s16
	s_addc_u32 s23, s23, s17
	v_lshlrev_b32_e32 v140, 2, v142
	s_min_u32 s100, s82, 0x7ff
	s_lshl_b32 s100, s100, 10
	v_and_b32_e32 v210, 7, v0
	v_lshlrev_b32_e32 v210, 7, v210
	v_add_u32_e32 v210, s100, v210
	s_mov_b32 s100, s68
	s_mov_b32 s101, s72
	global_load_dword v211, v210, s[100:101]
	global_load_dword v150, v140, s[22:23] offset:64
	global_load_dword v149, v140, s[22:23] offset:128
	global_load_dword v148, v140, s[22:23] offset:192
	global_load_dword v147, v140, s[22:23] offset:512
	global_load_dword v146, v140, s[22:23] offset:576
	global_load_dword v145, v140, s[22:23] offset:640
	global_load_dword v144, v140, s[22:23] offset:704
	v_mul_f32_e32 v129, v129, v129
	v_mul_f32_e32 v125, v125, v125
	v_mul_f32_e32 v121, v121, v121
	v_mul_f32_e32 v117, v117, v117
	v_fmac_f32_e32 v129, v128, v128
	v_mul_f32_e32 v128, v131, v131
	v_fmac_f32_e32 v125, v124, v124
	v_mul_f32_e32 v124, v127, v127
	v_fmac_f32_e32 v121, v120, v120
	v_mul_f32_e32 v120, v123, v123
	v_fmac_f32_e32 v117, v116, v116
	v_mul_f32_e32 v116, v119, v119
	v_fmac_f32_e32 v128, v130, v130
	v_fmac_f32_e32 v124, v126, v126
	v_fmac_f32_e32 v120, v122, v122
	v_fmac_f32_e32 v116, v118, v118
	v_add_f32_e32 v128, v129, v128
	v_add_f32_e32 v124, v125, v124
	v_add_f32_e32 v120, v121, v120
	v_add_f32_e32 v116, v117, v116
	v_add_f32_e32 v124, v128, v124
	v_add_f32_e32 v116, v120, v116
	v_add_f32_e32 v117, v124, v116
	v_mov_b32_e32 v118, v117
	s_nop 1
	v_permlane16_swap_b32 v118, v117
	v_and_b32_e32 v152, 64, v236
	v_xor_b32_e32 v151, 32, v236
	v_add_u32_e32 v152, 64, v152
	v_cmp_lt_i32_e32 vcc, v151, v152
	s_lshl_b32 s9, s83, 2
	s_or_b32 s24, s24, s9
	v_cndmask_b32_e32 v116, v236, v151, vcc
	s_lshl_b64 s[0:1], s[0:1], 8
	v_lshlrev_b32_e32 v116, 2, v116
	s_waitcnt lgkmcnt(0)
	v_add_f32_e32 v117, v117, v118
	s_add_u32 s0, s0, s14
	v_mov_b32_e32 v118, v117
	s_nop 1
	v_permlane32_swap_b32 v118, v117
	s_addc_u32 s1, s1, s15
	s_ashr_i32 s25, s24, 31
	v_or_b32_e32 v143, s0, v142
	v_mov_b32_e32 v142, s1
	s_lshl_b64 s[0:1], s[24:25], 2
	v_and_b32_e32 v119, 48, v141
	s_add_u32 s0, s73, s0
	v_cmp_eq_u32_e64 s[16:17], 0, v119
	s_addc_u32 s1, s74, s1
	s_and_saveexec_b64 s[14:15], s[16:17]
	s_cbranch_execz .LBB0_3053
	v_mov_b32_e32 v141, v2
	v_lshl_add_u64 v[120:121], s[22:23], 0, v[140:141]
	global_load_dword v119, v[120:121], off
	s_waitcnt lgkmcnt(0)
	v_add_f32_e32 v117, v117, v118
	s_waitcnt vmcnt(0)
	v_add_f32_e32 v117, v117, v119
	v_fmamk_f32 v117, v117, 0x3c2aaaab, v231
	v_cmp_gt_f32_e32 vcc, s11, v117
	v_mul_f32_e32 v118, 0x4b800000, v117
	s_nop 0
	v_cndmask_b32_e32 v117, v117, v118, vcc
	v_rsq_f32_e32 v117, v117
	s_nop 0
	v_mul_f32_e32 v118, 0x45800000, v117
	v_cndmask_b32_e32 v117, v117, v118, vcc
	v_mad_u64_u32 v[118:119], s[22:23], v143, 48, s[0:1]
	v_mov_b32_e32 v120, v119
	v_mad_u64_u32 v[120:121], s[22:23], v142, 48, v[120:121]
	v_mov_b32_e32 v119, v120
	global_store_dword v[118:119], v117, off
